# ph0 converts only layer-0 weights; layer l+1 weights converted by idle WGs (bid>=128) at end of layer l FFN-in phases
# speedup vs baseline: 1.0111x; 1.0065x over previous
.LBB0_697:
	s_movk_i32 s98, 0x3100
.Ltr_entry:
	s_cmp_ge_i32 s17, s98
	s_mov_b32 s57, s39
	s_cbranch_scc1 .LBB0_743
	s_mul_hi_i32 s0, s17, 0x5397829d
	s_lshr_b32 s1, s0, 31
	s_ashr_i32 s0, s0, 12
	s_add_i32 s6, s0, s1
	s_mul_i32 s0, s6, 0x3100
	s_sub_i32 s18, s17, s0
	s_ashr_i32 s7, s6, 31
	s_mul_i32 s1, s6, 0x3680000
	s_mul_hi_i32 s0, s6, 0x3680000
	s_add_u32 s5, s78, s1
	s_addc_u32 s9, s79, s0
	s_cmpk_gt_i32 s18, 0x15ff
	s_cbranch_scc0 .LBB0_712
	s_cmpk_gt_u32 s18, 0x20ff
	s_cbranch_scc0 .LBB0_713
	s_cmpk_gt_u32 s18, 0x2cff
	s_mov_b64 s[14:15], -1
	s_cbranch_scc0 .LBB0_709
	s_cmpk_gt_u32 s18, 0x2dff
	s_cbranch_scc0 .LBB0_706
	s_cmpk_gt_u32 s18, 0x2eff
	s_mov_b64 s[10:11], -1
	s_cbranch_scc0 .LBB0_704
	v_readlane_b32 s0, v253, 57
	s_nop 1
	v_mov_b32_e32 v0, s0
	ds_read_b64 v[0:1], v0
	s_lshl_b64 s[0:1], s[6:7], 22
	s_waitcnt lgkmcnt(0)
	v_readfirstlane_b32 s8, v0
	v_readfirstlane_b32 s4, v1
	s_add_u32 s12, s8, s0
	s_addc_u32 s13, s4, s1
	s_add_u32 s0, s5, 0x2f80000
	s_addc_u32 s1, s9, 0
	s_lshl_b32 s4, s18, 5
	s_lshl_b32 s10, s18, 1
	s_and_b32 s8, s4, 0x3e0
	s_and_b32 s4, s10, 0x7fffffc0
	s_addk_i32 s4, 0xa200
	s_mov_b64 s[10:11], 0

.LBB0_719:
	s_cmp_lt_i32 s22, s98
	s_cselect_b64 s[8:9], -1, 0
	s_cmp_ge_i32 s22, s98
	s_cbranch_scc1 .LBB0_740
	s_mul_hi_i32 s5, s22, 0x5397829d
	s_lshr_b32 s6, s5, 31
	s_ashr_i32 s5, s5, 12
	s_add_i32 s10, s5, s6
	s_mul_i32 s5, s10, 0xffffcf00
	s_add_i32 s37, s22, s5
	s_ashr_i32 s11, s10, 31
	s_mul_i32 s5, s10, 0x3680000
	s_mul_hi_i32 s6, s10, 0x3680000
	s_add_u32 s5, s78, s5
	s_addc_u32 s13, s79, s6
	s_cmpk_gt_i32 s37, 0x15ff
	s_cbranch_scc0 .LBB0_734
	s_cmpk_gt_u32 s37, 0x20ff
	s_cbranch_scc0 .LBB0_735
	s_cmpk_gt_u32 s37, 0x2cff
	s_mov_b64 s[18:19], -1
	s_cbranch_scc0 .LBB0_731
	s_cmpk_gt_u32 s37, 0x2dff
	s_cbranch_scc0 .LBB0_728
	s_cmpk_gt_u32 s37, 0x2eff
	s_mov_b64 s[14:15], -1
	s_cbranch_scc0 .LBB0_726
	v_readlane_b32 s6, v253, 57
	s_mul_i32 s14, s10, 0xffff9e00
	s_nop 0
	v_mov_b32_e32 v32, s6
	ds_read_b64 v[32:33], v32
	s_lshl_b64 s[6:7], s[10:11], 22
	s_waitcnt lgkmcnt(0)
	v_readfirstlane_b32 s15, v32
	v_readfirstlane_b32 s12, v33
	s_add_u32 s16, s15, s6
	s_addc_u32 s17, s12, s7
	s_add_u32 s6, s5, 0x2f80000
	s_addc_u32 s7, s13, 0
	s_add_i32 s14, s23, s14
	s_and_b32 s14, s14, 0x7fffffc0
	s_and_b32 s12, s25, 0x3e0
	s_add_i32 s34, s14, 0xffffa200
	s_mov_b64 s[14:15], 0

.Ldef_check:
	s_cmp_lt_i32 s44, 2
	s_cbranch_scc1 .LBB0_743
	s_add_i32 s0, s44, -2
	s_mul_i32 s1, s0, 47
	s_lshr_b32 s1, s1, 9
	s_mul_i32 s4, s1, 11
	s_sub_i32 s0, s0, s4
	s_cmp_gt_i32 s1, 2
	s_cbranch_scc1 .LBB0_743
	v_readlane_b32 s5, v254, 63
	s_cmp_lt_i32 s5, 0x80
	s_cbranch_scc1 .LBB0_743
	s_cmp_eq_u32 s0, 0
	s_cbranch_scc1 .Ldef_go0
	s_cmp_eq_u32 s0, 8
	s_cbranch_scc0 .LBB0_743
	s_movk_i32 s4, 0x400
	s_branch .Ldef_go
.Ldef_go0:
	s_mov_b32 s4, 0
.Ldef_go:
	s_add_i32 s1, s1, 1
	s_mul_i32 s17, s1, 0x3100
	s_add_i32 s98, s17, 0x3100
	v_mov_b32_e32 v84, v244
	v_and_b32_e32 v83, 63, v244
	v_readlane_b32 s64, v254, 28
	v_readfirstlane_b32 s16, v84
	s_add_i32 s5, s5, 0xffffff80
	s_ashr_i32 s16, s16, 6
	s_lshl_b32 s5, s5, 3
	s_add_i32 s5, s5, s16
	s_add_i32 s17, s17, s5
	s_add_i32 s17, s17, s4
	s_branch .Ltr_entry

	.amdhsa_kernel _Z4mega4Args
		.amdhsa_group_segment_fixed_size 0
		.amdhsa_private_segment_fixed_size 0
		.amdhsa_kernarg_size 488
		.amdhsa_user_sgpr_count 2
		.amdhsa_user_sgpr_dispatch_ptr 0
		.amdhsa_user_sgpr_queue_ptr 0
		.amdhsa_user_sgpr_kernarg_segment_ptr 1
		.amdhsa_user_sgpr_dispatch_id 0
		.amdhsa_user_sgpr_kernarg_preload_length 0
		.amdhsa_user_sgpr_kernarg_preload_offset 0
		.amdhsa_user_sgpr_private_segment_size 0
		.amdhsa_uses_dynamic_stack 0
		.amdhsa_enable_private_segment 0
		.amdhsa_system_sgpr_workgroup_id_x 1
		.amdhsa_system_sgpr_workgroup_id_y 0
		.amdhsa_system_sgpr_workgroup_id_z 0
		.amdhsa_system_sgpr_workgroup_info 0
		.amdhsa_system_vgpr_workitem_id 2
		.amdhsa_next_free_vgpr 256
		.amdhsa_next_free_sgpr 100
		.amdhsa_accum_offset 256
		.amdhsa_reserve_vcc 1
		.amdhsa_float_round_mode_32 0
		.amdhsa_float_round_mode_16_64 0
		.amdhsa_float_denorm_mode_32 3
		.amdhsa_float_denorm_mode_16_64 3
		.amdhsa_dx10_clamp 1
		.amdhsa_ieee_mode 1
		.amdhsa_fp16_overflow 0
		.amdhsa_tg_split 0
		.amdhsa_exception_fp_ieee_invalid_op 0
		.amdhsa_exception_fp_denorm_src 0
		.amdhsa_exception_fp_ieee_div_zero 0
		.amdhsa_exception_fp_ieee_overflow 0
		.amdhsa_exception_fp_ieee_underflow 0
		.amdhsa_exception_fp_ieee_inexact 0
		.amdhsa_exception_int_div_zero 0
	.end_amdhsa_kernel

amdhsa.kernels:
  - .agpr_count:     0
    .args:
      - .offset:         0
        .size:           232
        .value_kind:     by_value
      - .offset:         232
        .size:           4
        .value_kind:     hidden_block_count_x
      - .offset:         236
        .size:           4
        .value_kind:     hidden_block_count_y
      - .offset:         240
        .size:           4
        .value_kind:     hidden_block_count_z
      - .offset:         244
        .size:           2
        .value_kind:     hidden_group_size_x
      - .offset:         246
        .size:           2
        .value_kind:     hidden_group_size_y
      - .offset:         248
        .size:           2
        .value_kind:     hidden_group_size_z
      - .offset:         250
        .size:           2
        .value_kind:     hidden_remainder_x
      - .offset:         252
        .size:           2
        .value_kind:     hidden_remainder_y
      - .offset:         254
        .size:           2
        .value_kind:     hidden_remainder_z
      - .offset:         272
        .size:           8
        .value_kind:     hidden_global_offset_x
      - .offset:         280
        .size:           8
        .value_kind:     hidden_global_offset_y
      - .offset:         288
        .size:           8
        .value_kind:     hidden_global_offset_z
      - .offset:         296
        .size:           2
        .value_kind:     hidden_grid_dims
      - .offset:         320
        .size:           8
        .value_kind:     hidden_multigrid_sync_arg
      - .offset:         352
        .size:           4
        .value_kind:     hidden_dynamic_lds_size
    .group_segment_fixed_size: 0
    .kernarg_segment_align: 8
    .kernarg_segment_size: 488
    .language:       OpenCL C
    .language_version:
      - 2
      - 0
    .max_flat_workgroup_size: 512
    .name:           _Z4mega4Args
    .private_segment_fixed_size: 0
    .sgpr_count:     106
    .sgpr_spill_count: 169
    .symbol:         _Z4mega4Args.kd
    .uniform_work_group_size: 1
    .uses_dynamic_stack: false
    .vgpr_count:     256
    .vgpr_spill_count: 0
    .wavefront_size: 64
